# adds: GEMM2 K-loop first trip peeled as well
# speedup vs baseline: 1.4860x; 1.0038x over previous
.LBB0_934:
	s_ashr_i32 s31, s30, 31
	v_cmp_lt_i64_e32 vcc, s[12:13], v[162:163]
	s_lshl_b64 s[12:13], s[30:31], 19
	s_add_u32 s94, s62, s12
	s_addc_u32 s95, s63, s13
	s_and_b64 s[12:13], vcc, exec
	s_cselect_b32 s31, s95, s3
	s_cselect_b32 s4, s94, s2
	s_ashr_i32 s11, s10, 31
	s_lshl_b64 s[12:13], s[10:11], 19
	s_add_u32 s16, s5, s12
	s_addc_u32 s17, s6, s13
	s_and_b64 s[12:13], vcc, exec
	s_cselect_b32 s11, s17, s35
	s_cselect_b32 vcc_lo, s16, s34
	s_add_u32 s12, s2, 0x40080
	s_addc_u32 s13, s3, 0
	s_add_u32 s34, s34, 0x100
	s_addc_u32 s35, s35, 0
	s_mov_b32 vcc_hi, -2
	s_waitcnt lgkmcnt(0)
	s_add_u32 s2, s12, 0xfffc0080
	s_addc_u32 s3, s13, -1
	s_add_i32 s38, 32, 0x10000
	v_add_u32_e32 v152, s38, v145
	ds_read_b128 v[140:143], v152
	ds_read_b128 v[148:151], v152 offset:1024
	ds_read_b128 v[164:167], v152 offset:2048
	ds_read_b128 v[168:171], v152 offset:3072
	s_cmp_eq_u32 vcc_hi, 12
	s_cselect_b32 s3, s31, s3
	s_cselect_b32 s2, s4, s2
	s_cselect_b32 s19, s11, s35
	s_cselect_b32 s18, vcc_lo, s34
	v_lshl_add_u64 v[152:153], s[12:13], 0, v[136:137]
	s_add_i32 m0, s14, 0xc000
	ds_read_b128 v[172:175], v147
	ds_read_b128 v[176:179], v147 offset:1024
	ds_read_b128 v[182:185], v147 offset:2048
	ds_read_b128 v[186:189], v147 offset:3072
	ds_read_b128 v[190:193], v147 offset:4096
	ds_read_b128 v[194:197], v147 offset:5120
	ds_read_b128 v[198:201], v147 offset:6144
	ds_read_b128 v[202:205], v147 offset:7168
	global_load_lds_dwordx4 v[152:153], off
	v_lshl_add_u64 v[152:153], s[12:13], 0, v[138:139]
	s_add_i32 m0, s14, 0xe000
	s_nop 0
	global_load_lds_dwordx4 v[152:153], off
	s_waitcnt lgkmcnt(8)
	s_barrier
	s_waitcnt lgkmcnt(0)
	s_waitcnt lgkmcnt(0)
	v_mfma_f32_16x16x32_bf16 v[126:129], v[140:143], v[172:175], 0
	v_mfma_f32_16x16x32_bf16 v[122:125], v[164:167], v[172:175], 0
	v_mfma_f32_16x16x32_bf16 v[110:113], v[140:143], v[182:185], 0
	v_mfma_f32_16x16x32_bf16 v[106:109], v[164:167], v[182:185], 0
	v_mfma_f32_16x16x32_bf16 v[94:97], v[140:143], v[190:193], 0
	v_mfma_f32_16x16x32_bf16 v[90:93], v[164:167], v[190:193], 0
	v_mfma_f32_16x16x32_bf16 v[78:81], v[140:143], v[198:201], 0
	v_mfma_f32_16x16x32_bf16 v[74:77], v[164:167], v[198:201], 0
	v_mfma_f32_16x16x32_bf16 v[126:129], v[148:151], v[176:179], v[126:129]
	v_mfma_f32_16x16x32_bf16 v[122:125], v[168:171], v[176:179], v[122:125]
	v_mfma_f32_16x16x32_bf16 v[110:113], v[148:151], v[186:189], v[110:113]
	v_mfma_f32_16x16x32_bf16 v[106:109], v[168:171], v[186:189], v[106:109]
	v_mfma_f32_16x16x32_bf16 v[94:97], v[148:151], v[194:197], v[94:97]
	v_mfma_f32_16x16x32_bf16 v[90:93], v[168:171], v[194:197], v[90:93]
	v_mfma_f32_16x16x32_bf16 v[78:81], v[148:151], v[202:205], v[78:81]
	v_mfma_f32_16x16x32_bf16 v[74:77], v[168:171], v[202:205], v[74:77]
	s_barrier
	s_add_i32 s24, 32, 0x14000
	v_add_u32_e32 v152, s24, v145
	s_add_i32 s38, s38, s7
	ds_read_b128 v[206:209], v152
	ds_read_b128 v[210:213], v152 offset:1024
	ds_read_b128 v[214:217], v152 offset:2048
	ds_read_b128 v[218:221], v152 offset:3072
	v_lshl_add_u64 v[152:153], s[18:19], 0, v[154:155]
	s_mov_b32 m0, s38
	v_lshl_add_u64 v[222:223], s[18:19], 0, v[130:131]
	global_load_lds_dwordx4 v[152:153], off
	s_add_i32 m0, s38, 0x2000
	s_nop 0
	global_load_lds_dwordx4 v[222:223], off
	s_barrier
	s_waitcnt lgkmcnt(0)
	s_waitcnt lgkmcnt(0)
	v_mfma_f32_16x16x32_bf16 v[118:121], v[206:209], v[172:175], 0
	v_mfma_f32_16x16x32_bf16 v[114:117], v[214:217], v[172:175], 0
	v_mfma_f32_16x16x32_bf16 v[102:105], v[206:209], v[182:185], 0
	v_mfma_f32_16x16x32_bf16 v[98:101], v[214:217], v[182:185], 0
	v_mfma_f32_16x16x32_bf16 v[86:89], v[206:209], v[190:193], 0
	v_mfma_f32_16x16x32_bf16 v[82:85], v[214:217], v[190:193], 0
	v_mfma_f32_16x16x32_bf16 v[70:73], v[206:209], v[198:201], 0
	v_mfma_f32_16x16x32_bf16 v[66:69], v[214:217], v[198:201], 0
	v_mfma_f32_16x16x32_bf16 v[118:121], v[210:213], v[176:179], v[118:121]
	v_mfma_f32_16x16x32_bf16 v[114:117], v[218:221], v[176:179], v[114:117]
	v_mfma_f32_16x16x32_bf16 v[102:105], v[210:213], v[186:189], v[102:105]
	v_mfma_f32_16x16x32_bf16 v[98:101], v[218:221], v[186:189], v[98:101]
	v_mfma_f32_16x16x32_bf16 v[86:89], v[210:213], v[194:197], v[86:89]
	v_mfma_f32_16x16x32_bf16 v[82:85], v[218:221], v[194:197], v[82:85]
	v_mfma_f32_16x16x32_bf16 v[70:73], v[210:213], v[202:205], v[70:73]
	v_mfma_f32_16x16x32_bf16 v[66:69], v[218:221], v[202:205], v[66:69]
	s_mov_b32 m0, s14
	v_lshl_add_u64 v[224:225], s[2:3], 0, v[134:135]
	s_barrier
	ds_read_b128 v[172:175], v147 offset:16384
	ds_read_b128 v[176:179], v147 offset:17408
	ds_read_b128 v[182:185], v147 offset:18432
	ds_read_b128 v[186:189], v147 offset:19456
	ds_read_b128 v[190:193], v147 offset:20480
	ds_read_b128 v[194:197], v147 offset:21504
	ds_read_b128 v[198:201], v147 offset:22528
	ds_read_b128 v[202:205], v147 offset:23552
	global_load_lds_dwordx4 v[224:225], off
	v_lshl_add_u64 v[226:227], s[2:3], 0, v[132:133]
	s_mov_b32 m0, s20
	s_nop 0
	global_load_lds_dwordx4 v[226:227], off
	s_barrier
	s_waitcnt lgkmcnt(0)
	s_waitcnt lgkmcnt(0)
	v_mfma_f32_16x16x32_bf16 v[62:65], v[140:143], v[172:175], 0
	v_mfma_f32_16x16x32_bf16 v[58:61], v[164:167], v[172:175], 0
	v_mfma_f32_16x16x32_bf16 v[46:49], v[140:143], v[182:185], 0
	v_mfma_f32_16x16x32_bf16 v[42:45], v[164:167], v[182:185], 0
	v_mfma_f32_16x16x32_bf16 v[30:33], v[140:143], v[190:193], 0
	v_mfma_f32_16x16x32_bf16 v[26:29], v[164:167], v[190:193], 0
	v_mfma_f32_16x16x32_bf16 v[14:17], v[140:143], v[198:201], 0
	v_mfma_f32_16x16x32_bf16 v[10:13], v[164:167], v[198:201], 0
	v_mfma_f32_16x16x32_bf16 v[62:65], v[148:151], v[176:179], v[62:65]
	v_mfma_f32_16x16x32_bf16 v[58:61], v[168:171], v[176:179], v[58:61]
	v_mfma_f32_16x16x32_bf16 v[46:49], v[148:151], v[186:189], v[46:49]
	v_mfma_f32_16x16x32_bf16 v[42:45], v[168:171], v[186:189], v[42:45]
	v_mfma_f32_16x16x32_bf16 v[30:33], v[148:151], v[194:197], v[30:33]
	v_mfma_f32_16x16x32_bf16 v[26:29], v[168:171], v[194:197], v[26:29]
	v_mfma_f32_16x16x32_bf16 v[14:17], v[148:151], v[202:205], v[14:17]
	v_mfma_f32_16x16x32_bf16 v[10:13], v[168:171], v[202:205], v[10:13]
	s_barrier
	s_add_u32 s38, s18, 0x40000
	s_addc_u32 s39, s19, 0
	s_add_i32 s24, s24, s7
	v_lshl_add_u64 v[140:141], s[38:39], 0, v[154:155]
	s_mov_b32 m0, s24
	s_nop 0
	global_load_lds_dwordx4 v[140:141], off
	v_lshl_add_u64 v[140:141], s[38:39], 0, v[130:131]
	s_add_i32 m0, s24, 0x2000
	s_nop 0
	global_load_lds_dwordx4 v[140:141], off
	s_waitcnt vmcnt(6)
	s_barrier
	v_mfma_f32_16x16x32_bf16 v[54:57], v[206:209], v[172:175], 0
	v_mfma_f32_16x16x32_bf16 v[50:53], v[214:217], v[172:175], 0
	v_mfma_f32_16x16x32_bf16 v[38:41], v[206:209], v[182:185], 0
	v_mfma_f32_16x16x32_bf16 v[34:37], v[214:217], v[182:185], 0
	v_mfma_f32_16x16x32_bf16 v[22:25], v[206:209], v[190:193], 0
	v_mfma_f32_16x16x32_bf16 v[18:21], v[214:217], v[190:193], 0
	v_mfma_f32_16x16x32_bf16 v[6:9], v[206:209], v[198:201], 0
	v_mfma_f32_16x16x32_bf16 v[2:5], v[214:217], v[198:201], 0
	v_mfma_f32_16x16x32_bf16 v[54:57], v[210:213], v[176:179], v[54:57]
	v_mfma_f32_16x16x32_bf16 v[50:53], v[218:221], v[176:179], v[50:53]
	v_mfma_f32_16x16x32_bf16 v[38:41], v[210:213], v[186:189], v[38:41]
	v_mfma_f32_16x16x32_bf16 v[34:37], v[218:221], v[186:189], v[34:37]
	v_mfma_f32_16x16x32_bf16 v[22:25], v[210:213], v[194:197], v[22:25]
	v_mfma_f32_16x16x32_bf16 v[18:21], v[218:221], v[194:197], v[18:21]
	v_mfma_f32_16x16x32_bf16 v[6:9], v[210:213], v[202:205], v[6:9]
	v_mfma_f32_16x16x32_bf16 v[2:5], v[218:221], v[202:205], v[2:5]
	s_add_i32 s24, 32, 0x18000
	v_add_u32_e32 v168, s24, v145
	s_barrier
	ds_read_b128 v[140:143], v168
	ds_read_b128 v[148:151], v168 offset:1024
	ds_read_b128 v[164:167], v168 offset:2048
	ds_read_b128 v[168:171], v168 offset:3072
	s_add_u32 s2, s2, 0x40000
	s_addc_u32 s3, s3, 0
	s_mov_b32 m0, s21
	v_lshl_add_u64 v[206:207], s[2:3], 0, v[134:135]
	ds_read_b128 v[172:175], v147 offset:32768
	ds_read_b128 v[176:179], v147 offset:33792
	ds_read_b128 v[182:185], v147 offset:34816
	ds_read_b128 v[186:189], v147 offset:35840
	ds_read_b128 v[190:193], v147 offset:36864
	ds_read_b128 v[194:197], v147 offset:37888
	ds_read_b128 v[198:201], v147 offset:38912
	ds_read_b128 v[202:205], v147 offset:39936
	global_load_lds_dwordx4 v[206:207], off
	v_lshl_add_u64 v[206:207], s[2:3], 0, v[132:133]
	s_mov_b32 m0, s22
	s_nop 0
	global_load_lds_dwordx4 v[206:207], off
	s_waitcnt lgkmcnt(8)
	s_barrier
	s_waitcnt lgkmcnt(0)
	s_waitcnt lgkmcnt(0)
	v_mfma_f32_16x16x32_bf16 v[126:129], v[140:143], v[172:175], v[126:129]
	v_mfma_f32_16x16x32_bf16 v[122:125], v[164:167], v[172:175], v[122:125]
	v_mfma_f32_16x16x32_bf16 v[110:113], v[140:143], v[182:185], v[110:113]
	v_mfma_f32_16x16x32_bf16 v[106:109], v[164:167], v[182:185], v[106:109]
	v_mfma_f32_16x16x32_bf16 v[94:97], v[140:143], v[190:193], v[94:97]
	v_mfma_f32_16x16x32_bf16 v[90:93], v[164:167], v[190:193], v[90:93]
	v_mfma_f32_16x16x32_bf16 v[78:81], v[140:143], v[198:201], v[78:81]
	v_mfma_f32_16x16x32_bf16 v[74:77], v[164:167], v[198:201], v[74:77]
	v_mfma_f32_16x16x32_bf16 v[126:129], v[148:151], v[176:179], v[126:129]
	v_mfma_f32_16x16x32_bf16 v[122:125], v[168:171], v[176:179], v[122:125]
	v_mfma_f32_16x16x32_bf16 v[110:113], v[148:151], v[186:189], v[110:113]
	v_mfma_f32_16x16x32_bf16 v[106:109], v[168:171], v[186:189], v[106:109]
	v_mfma_f32_16x16x32_bf16 v[94:97], v[148:151], v[194:197], v[94:97]
	v_mfma_f32_16x16x32_bf16 v[90:93], v[168:171], v[194:197], v[90:93]
	v_mfma_f32_16x16x32_bf16 v[78:81], v[148:151], v[202:205], v[78:81]
	v_mfma_f32_16x16x32_bf16 v[74:77], v[168:171], v[202:205], v[74:77]
	s_barrier
	s_add_i32 s38, 32, 0x1c000
	s_add_i32 s2, s24, s7
	v_add_u32_e32 v218, s38, v145
	v_lshl_add_u64 v[152:153], v[152:153], 0, s[44:45]
	s_mov_b32 m0, s2
	ds_read_b128 v[206:209], v218
	ds_read_b128 v[210:213], v218 offset:1024
	ds_read_b128 v[214:217], v218 offset:2048
	ds_read_b128 v[218:221], v218 offset:3072
	global_load_lds_dwordx4 v[152:153], off
	v_lshl_add_u64 v[152:153], v[222:223], 0, s[44:45]
	s_add_i32 m0, s2, 0x2000
	s_nop 0
	global_load_lds_dwordx4 v[152:153], off
	s_barrier
	s_waitcnt lgkmcnt(0)
	s_waitcnt lgkmcnt(0)
	v_mfma_f32_16x16x32_bf16 v[118:121], v[206:209], v[172:175], v[118:121]
	v_mfma_f32_16x16x32_bf16 v[114:117], v[214:217], v[172:175], v[114:117]
	v_mfma_f32_16x16x32_bf16 v[102:105], v[206:209], v[182:185], v[102:105]
	v_mfma_f32_16x16x32_bf16 v[98:101], v[214:217], v[182:185], v[98:101]
	v_mfma_f32_16x16x32_bf16 v[86:89], v[206:209], v[190:193], v[86:89]
	v_mfma_f32_16x16x32_bf16 v[82:85], v[214:217], v[190:193], v[82:85]
	v_mfma_f32_16x16x32_bf16 v[70:73], v[206:209], v[198:201], v[70:73]
	v_mfma_f32_16x16x32_bf16 v[66:69], v[214:217], v[198:201], v[66:69]
	v_mfma_f32_16x16x32_bf16 v[118:121], v[210:213], v[176:179], v[118:121]
	v_mfma_f32_16x16x32_bf16 v[114:117], v[218:221], v[176:179], v[114:117]
	v_mfma_f32_16x16x32_bf16 v[102:105], v[210:213], v[186:189], v[102:105]
	v_mfma_f32_16x16x32_bf16 v[98:101], v[218:221], v[186:189], v[98:101]
	v_mfma_f32_16x16x32_bf16 v[86:89], v[210:213], v[194:197], v[86:89]
	v_mfma_f32_16x16x32_bf16 v[82:85], v[218:221], v[194:197], v[82:85]
	v_mfma_f32_16x16x32_bf16 v[70:73], v[210:213], v[202:205], v[70:73]
	v_mfma_f32_16x16x32_bf16 v[66:69], v[218:221], v[202:205], v[66:69]
	s_mov_b32 m0, s23
	v_lshl_add_u64 v[152:153], v[224:225], 0, s[44:45]
	s_barrier
	ds_read_b128 v[172:175], v147 offset:49152
	ds_read_b128 v[176:179], v147 offset:50176
	ds_read_b128 v[182:185], v147 offset:51200
	ds_read_b128 v[186:189], v147 offset:52224
	ds_read_b128 v[190:193], v147 offset:53248
	ds_read_b128 v[194:197], v147 offset:54272
	ds_read_b128 v[198:201], v147 offset:55296
	ds_read_b128 v[202:205], v147 offset:56320
	global_load_lds_dwordx4 v[152:153], off
	v_lshl_add_u64 v[152:153], v[226:227], 0, s[44:45]
	s_mov_b32 m0, s28
	s_nop 0
	global_load_lds_dwordx4 v[152:153], off
	s_barrier
	s_waitcnt lgkmcnt(0)
	s_waitcnt lgkmcnt(0)
	v_mfma_f32_16x16x32_bf16 v[62:65], v[140:143], v[172:175], v[62:65]
	v_mfma_f32_16x16x32_bf16 v[58:61], v[164:167], v[172:175], v[58:61]
	v_mfma_f32_16x16x32_bf16 v[46:49], v[140:143], v[182:185], v[46:49]
	v_mfma_f32_16x16x32_bf16 v[42:45], v[164:167], v[182:185], v[42:45]
	v_mfma_f32_16x16x32_bf16 v[30:33], v[140:143], v[190:193], v[30:33]
	v_mfma_f32_16x16x32_bf16 v[26:29], v[164:167], v[190:193], v[26:29]
	v_mfma_f32_16x16x32_bf16 v[14:17], v[140:143], v[198:201], v[14:17]
	v_mfma_f32_16x16x32_bf16 v[10:13], v[164:167], v[198:201], v[10:13]
	v_mfma_f32_16x16x32_bf16 v[62:65], v[148:151], v[176:179], v[62:65]
	v_mfma_f32_16x16x32_bf16 v[58:61], v[168:171], v[176:179], v[58:61]
	v_mfma_f32_16x16x32_bf16 v[46:49], v[148:151], v[186:189], v[46:49]
	v_mfma_f32_16x16x32_bf16 v[42:45], v[168:171], v[186:189], v[42:45]
	v_mfma_f32_16x16x32_bf16 v[30:33], v[148:151], v[194:197], v[30:33]
	v_mfma_f32_16x16x32_bf16 v[26:29], v[168:171], v[194:197], v[26:29]
	v_mfma_f32_16x16x32_bf16 v[14:17], v[148:151], v[202:205], v[14:17]
	v_mfma_f32_16x16x32_bf16 v[10:13], v[168:171], v[202:205], v[10:13]
	s_barrier
	s_add_u32 s2, s18, 0x40080
	s_addc_u32 s3, s19, 0
	s_add_i32 s18, s38, s7
	v_lshl_add_u64 v[140:141], s[2:3], 0, v[154:155]
	s_mov_b32 m0, s18
	s_nop 0
	global_load_lds_dwordx4 v[140:141], off
	v_lshl_add_u64 v[140:141], s[2:3], 0, v[130:131]
	s_add_i32 m0, s18, 0x2000
	s_nop 0
	global_load_lds_dwordx4 v[140:141], off
	s_waitcnt vmcnt(6)
	s_barrier
	v_mfma_f32_16x16x32_bf16 v[54:57], v[206:209], v[172:175], v[54:57]
	v_mfma_f32_16x16x32_bf16 v[50:53], v[214:217], v[172:175], v[50:53]
	v_mfma_f32_16x16x32_bf16 v[38:41], v[206:209], v[182:185], v[38:41]
	v_mfma_f32_16x16x32_bf16 v[34:37], v[214:217], v[182:185], v[34:37]
	v_mfma_f32_16x16x32_bf16 v[22:25], v[206:209], v[190:193], v[22:25]
	v_mfma_f32_16x16x32_bf16 v[18:21], v[214:217], v[190:193], v[18:21]
	v_mfma_f32_16x16x32_bf16 v[6:9], v[206:209], v[198:201], v[6:9]
	v_mfma_f32_16x16x32_bf16 v[2:5], v[214:217], v[198:201], v[2:5]
	v_mfma_f32_16x16x32_bf16 v[54:57], v[210:213], v[176:179], v[54:57]
	v_mfma_f32_16x16x32_bf16 v[50:53], v[218:221], v[176:179], v[50:53]
	v_mfma_f32_16x16x32_bf16 v[38:41], v[210:213], v[186:189], v[38:41]
	v_mfma_f32_16x16x32_bf16 v[34:37], v[218:221], v[186:189], v[34:37]
	v_mfma_f32_16x16x32_bf16 v[22:25], v[210:213], v[194:197], v[22:25]
	v_mfma_f32_16x16x32_bf16 v[18:21], v[218:221], v[194:197], v[18:21]
	v_mfma_f32_16x16x32_bf16 v[6:9], v[210:213], v[202:205], v[6:9]
	v_mfma_f32_16x16x32_bf16 v[2:5], v[218:221], v[202:205], v[2:5]
	s_add_i32 vcc_hi, vcc_hi, 2
	s_add_u32 s12, s12, 0x100
	s_addc_u32 s13, s13, 0
	s_add_u32 s34, s34, 0x100
	s_addc_u32 s35, s35, 0
	s_cmp_gt_u32 vcc_hi, 13
	s_barrier
